# v82 + phase-4 lag split: workgroups 128..191 lag 7 us, 192..255 lag 14 us
# speedup vs baseline: 1.0005x; 1.0005x over previous
.LBB0_589:
	s_cmp_gt_i32 s26, 4
	s_cselect_b64 s[4:5], -1, 0
	s_xor_b64 s[0:1], s[0:1], -1
	s_or_b64 s[0:1], s[4:5], s[0:1]
	s_and_b64 vcc, exec, s[0:1]
	s_cbranch_vccnz .LBB0_771
	s_cmpk_lt_u32 s96, 0x80
	s_cbranch_scc1 .Lp4_lag
	s_sleep 127
	s_sleep 127
	s_cmpk_lt_u32 s96, 0xc0
	s_cbranch_scc1 .Lp4_lag
	s_sleep 127
	s_sleep 127
